# WY producer step 1 (conv4 + silu + l2norm of the wave's 8 rows of q, k, v) rewritten by hand: 8 rows processed together with packed f32 silu and one DPP/permlane reduction tree instead of one serial c
# speedup vs baseline: 1.0120x; 1.0120x over previous
; #define LAS __attribute__((address_space(3)))
; __device__ __forceinline__ float bf2f(bf16 v) { return __uint_as_float(((unsigned)v) << 16); }
; __device__ __forceinline__ unsigned f2bf(float f) { unsigned u = __float_as_uint(f); return (u + 0x7fffu + ((u >> 16) & 1u)) >> 16; }
; __device__ __forceinline__ float siluf_(float x) { return x / (1.0f + __expf(-x)); }
; __device__ __forceinline__ int wy_producer_task(const Ctx& c, int l, int tk, WyPre& P, unsigned* head) {
;     ...
; #pragma unroll
;     for (int j = 0; j < 3; ++j) { float xv[11];
; #pragma unroll
;         for (int r = 0; r < 11; ++r) xv[r] = bf2f((bf16)P.hx[j][r]);
; #pragma unroll
;         for (int r = 0; r < 8; ++r) { const int i = 8 * wid + r;
;             float y = siluf_(P.cw[j][0] * xv[r] + P.cw[j][1] * xv[r + 1] + P.cw[j][2] * xv[r + 2] + P.cw[j][3] * xv[r + 3]);
;             if (j < 2) y *= rsqrtf(wave_sum_fast(y * y) + RMS_EPS) * (j == 0 ? 0.125f : 1.0f);
;             if (j == 0) QF[i * 65 + lane] = y;
;             else if (j == 1) { KF[i * 65 + lane] = y; *(LAS bf16*)(KIMG + (lane >> 3) * 1024 + i * 16 + (lane & 7) * 2) = (bf16)f2bf(y); }
;             else VF[i * 65 + lane] = y; } }
.LBB0_964:
	s_or_b64 exec, exec, s[2:3]
	v_readlane_b32 s1, v254, 46
	v_lshlrev_b32_e32 v2, 2, v88
	v_lshrrev_b32_e32 v4, 3, v88
	v_and_b32_e32 v5, 7, v88
	s_mul_i32 s2, s1, 0x820
	s_lshl_b32 s3, s1, 7
	v_lshlrev_b32_e32 v4, 10, v4
	v_add_u32_e32 v2, s2, v2
	v_lshl_add_u32 v4, v5, 1, v4
	v_add_u32_e32 v2, 0x400, v2
	v_add_u32_e32 v4, s3, v4
	v_add_u32_e32 v3, 0x11900, v2
	v_add_u32_e32 v4, 0x15e00, v4
	v_mov_b32_e32 v66, 0xbfb8aa3b
	v_mov_b32_e32 v67, 1.0
	v_and_b32_e32 v20, 0xffff0000, v114
	v_lshlrev_b32_e32 v21, 16, v114
	v_and_b32_e32 v22, 0xffff0000, v89
	v_lshlrev_b32_e32 v23, 16, v89
	v_and_b32_e32 v24, 0xffff0000, v115
	v_lshlrev_b32_e32 v25, 16, v115
	v_and_b32_e32 v26, 0xffff0000, v116
	v_lshlrev_b32_e32 v27, 16, v116
	v_and_b32_e32 v28, 0xffff0000, v117
	v_lshlrev_b32_e32 v29, 16, v117
	v_lshlrev_b32_e32 v30, 16, v94
	v_mul_f32_e32 v32, v85, v20
	v_mul_f32_e32 v33, v85, v21
	v_mul_f32_e32 v34, v85, v22
	v_mul_f32_e32 v35, v85, v23
	v_mul_f32_e32 v36, v85, v24
	v_mul_f32_e32 v37, v85, v25
	v_mul_f32_e32 v38, v85, v26
	v_mul_f32_e32 v39, v85, v27
	v_fmac_f32_e32 v32, v84, v21
	v_fmac_f32_e32 v33, v84, v22
	v_fmac_f32_e32 v34, v84, v23
	v_fmac_f32_e32 v35, v84, v24
	v_fmac_f32_e32 v36, v84, v25
	v_fmac_f32_e32 v37, v84, v26
	v_fmac_f32_e32 v38, v84, v27
	v_fmac_f32_e32 v39, v84, v28
	v_fmac_f32_e32 v32, v87, v22
	v_fmac_f32_e32 v33, v87, v23
	v_fmac_f32_e32 v34, v87, v24
	v_fmac_f32_e32 v35, v87, v25
	v_fmac_f32_e32 v36, v87, v26
	v_fmac_f32_e32 v37, v87, v27
	v_fmac_f32_e32 v38, v87, v28
	v_fmac_f32_e32 v39, v87, v29
	v_fmac_f32_e32 v32, v86, v23
	v_fmac_f32_e32 v33, v86, v24
	v_fmac_f32_e32 v34, v86, v25
	v_fmac_f32_e32 v35, v86, v26
	v_fmac_f32_e32 v36, v86, v27
	v_fmac_f32_e32 v37, v86, v28
	v_fmac_f32_e32 v38, v86, v29
	v_fmac_f32_e32 v39, v86, v30
	v_pk_mul_f32 v[40:41], v[32:33], v[66:67] op_sel_hi:[1,0]
	v_pk_mul_f32 v[42:43], v[34:35], v[66:67] op_sel_hi:[1,0]
	v_pk_mul_f32 v[44:45], v[36:37], v[66:67] op_sel_hi:[1,0]
	v_pk_mul_f32 v[46:47], v[38:39], v[66:67] op_sel_hi:[1,0]
	v_exp_f32_e32 v40, v40
	v_exp_f32_e32 v41, v41
	v_exp_f32_e32 v42, v42
	v_exp_f32_e32 v43, v43
	v_exp_f32_e32 v44, v44
	v_exp_f32_e32 v45, v45
	v_exp_f32_e32 v46, v46
	v_exp_f32_e32 v47, v47
	v_pk_add_f32 v[40:41], v[40:41], v[66:67] op_sel:[0,1] op_sel_hi:[1,1]
	v_pk_add_f32 v[42:43], v[42:43], v[66:67] op_sel:[0,1] op_sel_hi:[1,1]
	v_pk_add_f32 v[44:45], v[44:45], v[66:67] op_sel:[0,1] op_sel_hi:[1,1]
	v_pk_add_f32 v[46:47], v[46:47], v[66:67] op_sel:[0,1] op_sel_hi:[1,1]
	v_rcp_f32_e32 v40, v40
	v_rcp_f32_e32 v41, v41
	v_rcp_f32_e32 v42, v42
	v_rcp_f32_e32 v43, v43
	v_rcp_f32_e32 v44, v44
	v_rcp_f32_e32 v45, v45
	v_rcp_f32_e32 v46, v46
	v_rcp_f32_e32 v47, v47
	v_pk_mul_f32 v[32:33], v[32:33], v[40:41]
	v_pk_mul_f32 v[34:35], v[34:35], v[42:43]
	v_pk_mul_f32 v[36:37], v[36:37], v[44:45]
	v_pk_mul_f32 v[38:39], v[38:39], v[46:47]
	v_pk_mul_f32 v[48:49], v[32:33], v[32:33]
	v_pk_mul_f32 v[50:51], v[34:35], v[34:35]
	v_pk_mul_f32 v[52:53], v[36:37], v[36:37]
	v_pk_mul_f32 v[54:55], v[38:39], v[38:39]
	v_add_f32_dpp v48, v48, v48 quad_perm:[1,0,3,2] row_mask:0xf bank_mask:0xf bound_ctrl:1
	v_add_f32_dpp v49, v49, v49 quad_perm:[1,0,3,2] row_mask:0xf bank_mask:0xf bound_ctrl:1
	v_add_f32_dpp v50, v50, v50 quad_perm:[1,0,3,2] row_mask:0xf bank_mask:0xf bound_ctrl:1
	v_add_f32_dpp v51, v51, v51 quad_perm:[1,0,3,2] row_mask:0xf bank_mask:0xf bound_ctrl:1
	v_add_f32_dpp v52, v52, v52 quad_perm:[1,0,3,2] row_mask:0xf bank_mask:0xf bound_ctrl:1
	v_add_f32_dpp v53, v53, v53 quad_perm:[1,0,3,2] row_mask:0xf bank_mask:0xf bound_ctrl:1
	v_add_f32_dpp v54, v54, v54 quad_perm:[1,0,3,2] row_mask:0xf bank_mask:0xf bound_ctrl:1
	v_add_f32_dpp v55, v55, v55 quad_perm:[1,0,3,2] row_mask:0xf bank_mask:0xf bound_ctrl:1
	v_add_f32_dpp v48, v48, v48 quad_perm:[2,3,0,1] row_mask:0xf bank_mask:0xf bound_ctrl:1
	v_add_f32_dpp v49, v49, v49 quad_perm:[2,3,0,1] row_mask:0xf bank_mask:0xf bound_ctrl:1
	v_add_f32_dpp v50, v50, v50 quad_perm:[2,3,0,1] row_mask:0xf bank_mask:0xf bound_ctrl:1
	v_add_f32_dpp v51, v51, v51 quad_perm:[2,3,0,1] row_mask:0xf bank_mask:0xf bound_ctrl:1
	v_add_f32_dpp v52, v52, v52 quad_perm:[2,3,0,1] row_mask:0xf bank_mask:0xf bound_ctrl:1
	v_add_f32_dpp v53, v53, v53 quad_perm:[2,3,0,1] row_mask:0xf bank_mask:0xf bound_ctrl:1
	v_add_f32_dpp v54, v54, v54 quad_perm:[2,3,0,1] row_mask:0xf bank_mask:0xf bound_ctrl:1
	v_add_f32_dpp v55, v55, v55 quad_perm:[2,3,0,1] row_mask:0xf bank_mask:0xf bound_ctrl:1
	v_add_f32_dpp v48, v48, v48 row_half_mirror row_mask:0xf bank_mask:0xf bound_ctrl:1
	v_add_f32_dpp v49, v49, v49 row_half_mirror row_mask:0xf bank_mask:0xf bound_ctrl:1
	v_add_f32_dpp v50, v50, v50 row_half_mirror row_mask:0xf bank_mask:0xf bound_ctrl:1
	v_add_f32_dpp v51, v51, v51 row_half_mirror row_mask:0xf bank_mask:0xf bound_ctrl:1
	v_add_f32_dpp v52, v52, v52 row_half_mirror row_mask:0xf bank_mask:0xf bound_ctrl:1
	v_add_f32_dpp v53, v53, v53 row_half_mirror row_mask:0xf bank_mask:0xf bound_ctrl:1
	v_add_f32_dpp v54, v54, v54 row_half_mirror row_mask:0xf bank_mask:0xf bound_ctrl:1
	v_add_f32_dpp v55, v55, v55 row_half_mirror row_mask:0xf bank_mask:0xf bound_ctrl:1
	v_add_f32_dpp v48, v48, v48 row_mirror row_mask:0xf bank_mask:0xf bound_ctrl:1
	v_add_f32_dpp v49, v49, v49 row_mirror row_mask:0xf bank_mask:0xf bound_ctrl:1
	v_add_f32_dpp v50, v50, v50 row_mirror row_mask:0xf bank_mask:0xf bound_ctrl:1
	v_add_f32_dpp v51, v51, v51 row_mirror row_mask:0xf bank_mask:0xf bound_ctrl:1
	v_add_f32_dpp v52, v52, v52 row_mirror row_mask:0xf bank_mask:0xf bound_ctrl:1
	v_add_f32_dpp v53, v53, v53 row_mirror row_mask:0xf bank_mask:0xf bound_ctrl:1
; #define LAS __attribute__((address_space(3)))
; __device__ __forceinline__ float bf2f(bf16 v) { return __uint_as_float(((unsigned)v) << 16); }
; __device__ __forceinline__ unsigned f2bf(float f) { unsigned u = __float_as_uint(f); return (u + 0x7fffu + ((u >> 16) & 1u)) >> 16; }
; __device__ __forceinline__ float siluf_(float x) { return x / (1.0f + __expf(-x)); }
; __device__ __forceinline__ int wy_producer_task(const Ctx& c, int l, int tk, WyPre& P, unsigned* head) {
;     ...
; #pragma unroll
;     for (int j = 0; j < 3; ++j) { float xv[11];
; #pragma unroll
;         for (int r = 0; r < 11; ++r) xv[r] = bf2f((bf16)P.hx[j][r]);
; #pragma unroll
;         for (int r = 0; r < 8; ++r) { const int i = 8 * wid + r;
;             float y = siluf_(P.cw[j][0] * xv[r] + P.cw[j][1] * xv[r + 1] + P.cw[j][2] * xv[r + 2] + P.cw[j][3] * xv[r + 3]);
;             if (j < 2) y *= rsqrtf(wave_sum_fast(y * y) + RMS_EPS) * (j == 0 ? 0.125f : 1.0f);
;             if (j == 0) QF[i * 65 + lane] = y;
;             else if (j == 1) { KF[i * 65 + lane] = y; *(LAS bf16*)(KIMG + (lane >> 3) * 1024 + i * 16 + (lane & 7) * 2) = (bf16)f2bf(y); }
;             else VF[i * 65 + lane] = y; } }
	v_add_f32_dpp v54, v54, v54 row_mirror row_mask:0xf bank_mask:0xf bound_ctrl:1
	v_add_f32_dpp v55, v55, v55 row_mirror row_mask:0xf bank_mask:0xf bound_ctrl:1
	v_permlane16_swap_b32_e32 v48, v49
	v_permlane16_swap_b32_e32 v50, v51
	v_permlane16_swap_b32_e32 v52, v53
	v_permlane16_swap_b32_e32 v54, v55
	v_add_f32_e32 v48, v48, v49
	v_add_f32_e32 v50, v50, v51
	v_add_f32_e32 v52, v52, v53
	v_add_f32_e32 v54, v54, v55
	s_nop 1
	v_permlane32_swap_b32_e32 v48, v50
	v_permlane32_swap_b32_e32 v52, v54
	v_add_f32_e32 v48, v48, v50
	v_add_f32_e32 v52, v52, v54
	v_add_f32_e32 v48, 0x358637bd, v48
	v_add_f32_e32 v52, 0x358637bd, v52
	v_rsq_f32_e32 v48, v48
	v_rsq_f32_e32 v52, v52
	s_nop 0
	v_mul_f32_e32 v48, 0x3e000000, v48
	v_mul_f32_e32 v52, 0x3e000000, v52
	s_nop 1
	v_readlane_b32 s2, v48, 0
	v_readlane_b32 s3, v48, 16
	v_readlane_b32 s6, v48, 32
	v_readlane_b32 s7, v48, 48
	v_mul_f32_e32 v32, s2, v32
	v_mul_f32_e32 v33, s3, v33
	v_mul_f32_e32 v34, s6, v34
	v_mul_f32_e32 v35, s7, v35
	v_readlane_b32 s2, v52, 0
	v_readlane_b32 s3, v52, 16
	v_readlane_b32 s6, v52, 32
	v_readlane_b32 s7, v52, 48
	v_mul_f32_e32 v36, s2, v36
	v_mul_f32_e32 v37, s3, v37
	v_mul_f32_e32 v38, s6, v38
	v_mul_f32_e32 v39, s7, v39
	ds_write_b32 v2, v32 offset:16640
	ds_write_b32 v2, v33 offset:16900
	ds_write_b32 v2, v34 offset:17160
	ds_write_b32 v2, v35 offset:17420
	ds_write_b32 v2, v36 offset:17680
	ds_write_b32 v2, v37 offset:17940
	ds_write_b32 v2, v38 offset:18200
	ds_write_b32 v2, v39 offset:18460
	s_waitcnt vmcnt(4)
	v_and_b32_e32 v20, 0xffff0000, v119
	v_lshlrev_b32_e32 v21, 16, v119
	v_and_b32_e32 v22, 0xffff0000, v118
	v_lshlrev_b32_e32 v23, 16, v118
	v_and_b32_e32 v24, 0xffff0000, v120
	v_lshlrev_b32_e32 v25, 16, v120
	v_and_b32_e32 v26, 0xffff0000, v121
	v_lshlrev_b32_e32 v27, 16, v121
	v_and_b32_e32 v28, 0xffff0000, v122
	v_lshlrev_b32_e32 v29, 16, v122
	v_lshlrev_b32_e32 v30, 16, v96
	v_mul_f32_e32 v32, v91, v20
	v_mul_f32_e32 v33, v91, v21
	v_mul_f32_e32 v34, v91, v22
	v_mul_f32_e32 v35, v91, v23
	v_mul_f32_e32 v36, v91, v24
	v_mul_f32_e32 v37, v91, v25
	v_mul_f32_e32 v38, v91, v26
	v_mul_f32_e32 v39, v91, v27
	v_fmac_f32_e32 v32, v90, v21
	v_fmac_f32_e32 v33, v90, v22
	v_fmac_f32_e32 v34, v90, v23
	v_fmac_f32_e32 v35, v90, v24
	v_fmac_f32_e32 v36, v90, v25
	v_fmac_f32_e32 v37, v90, v26
	v_fmac_f32_e32 v38, v90, v27
	v_fmac_f32_e32 v39, v90, v28
	v_fmac_f32_e32 v32, v93, v22
	v_fmac_f32_e32 v33, v93, v23
	v_fmac_f32_e32 v34, v93, v24
	v_fmac_f32_e32 v35, v93, v25
	v_fmac_f32_e32 v36, v93, v26
	v_fmac_f32_e32 v37, v93, v27
	v_fmac_f32_e32 v38, v93, v28
	v_fmac_f32_e32 v39, v93, v29
	v_fmac_f32_e32 v32, v92, v23
	v_fmac_f32_e32 v33, v92, v24
	v_fmac_f32_e32 v34, v92, v25
	v_fmac_f32_e32 v35, v92, v26
	v_fmac_f32_e32 v36, v92, v27
	v_fmac_f32_e32 v37, v92, v28
	v_fmac_f32_e32 v38, v92, v29
	v_fmac_f32_e32 v39, v92, v30
	v_pk_mul_f32 v[40:41], v[32:33], v[66:67] op_sel_hi:[1,0]
	v_pk_mul_f32 v[42:43], v[34:35], v[66:67] op_sel_hi:[1,0]
	v_pk_mul_f32 v[44:45], v[36:37], v[66:67] op_sel_hi:[1,0]
	v_pk_mul_f32 v[46:47], v[38:39], v[66:67] op_sel_hi:[1,0]
	v_exp_f32_e32 v40, v40
	v_exp_f32_e32 v41, v41
	v_exp_f32_e32 v42, v42
	v_exp_f32_e32 v43, v43
	v_exp_f32_e32 v44, v44
	v_exp_f32_e32 v45, v45
	v_exp_f32_e32 v46, v46
	v_exp_f32_e32 v47, v47
	v_pk_add_f32 v[40:41], v[40:41], v[66:67] op_sel:[0,1] op_sel_hi:[1,1]
	v_pk_add_f32 v[42:43], v[42:43], v[66:67] op_sel:[0,1] op_sel_hi:[1,1]
	v_pk_add_f32 v[44:45], v[44:45], v[66:67] op_sel:[0,1] op_sel_hi:[1,1]
	v_pk_add_f32 v[46:47], v[46:47], v[66:67] op_sel:[0,1] op_sel_hi:[1,1]
	v_rcp_f32_e32 v40, v40
	v_rcp_f32_e32 v41, v41
	v_rcp_f32_e32 v42, v42
	v_rcp_f32_e32 v43, v43
	v_rcp_f32_e32 v44, v44
	v_rcp_f32_e32 v45, v45
	v_rcp_f32_e32 v46, v46
	v_rcp_f32_e32 v47, v47
	v_pk_mul_f32 v[32:33], v[32:33], v[40:41]
	v_pk_mul_f32 v[34:35], v[34:35], v[42:43]
	v_pk_mul_f32 v[36:37], v[36:37], v[44:45]
	v_pk_mul_f32 v[38:39], v[38:39], v[46:47]
	v_pk_mul_f32 v[48:49], v[32:33], v[32:33]
	v_pk_mul_f32 v[50:51], v[34:35], v[34:35]
	v_pk_mul_f32 v[52:53], v[36:37], v[36:37]
	v_pk_mul_f32 v[54:55], v[38:39], v[38:39]
	v_add_f32_dpp v48, v48, v48 quad_perm:[1,0,3,2] row_mask:0xf bank_mask:0xf bound_ctrl:1
	v_add_f32_dpp v49, v49, v49 quad_perm:[1,0,3,2] row_mask:0xf bank_mask:0xf bound_ctrl:1
	v_add_f32_dpp v50, v50, v50 quad_perm:[1,0,3,2] row_mask:0xf bank_mask:0xf bound_ctrl:1
	v_add_f32_dpp v51, v51, v51 quad_perm:[1,0,3,2] row_mask:0xf bank_mask:0xf bound_ctrl:1
	v_add_f32_dpp v52, v52, v52 quad_perm:[1,0,3,2] row_mask:0xf bank_mask:0xf bound_ctrl:1
	v_add_f32_dpp v53, v53, v53 quad_perm:[1,0,3,2] row_mask:0xf bank_mask:0xf bound_ctrl:1
	v_add_f32_dpp v54, v54, v54 quad_perm:[1,0,3,2] row_mask:0xf bank_mask:0xf bound_ctrl:1
	v_add_f32_dpp v55, v55, v55 quad_perm:[1,0,3,2] row_mask:0xf bank_mask:0xf bound_ctrl:1
	v_add_f32_dpp v48, v48, v48 quad_perm:[2,3,0,1] row_mask:0xf bank_mask:0xf bound_ctrl:1
	v_add_f32_dpp v49, v49, v49 quad_perm:[2,3,0,1] row_mask:0xf bank_mask:0xf bound_ctrl:1
	v_add_f32_dpp v50, v50, v50 quad_perm:[2,3,0,1] row_mask:0xf bank_mask:0xf bound_ctrl:1
	v_add_f32_dpp v51, v51, v51 quad_perm:[2,3,0,1] row_mask:0xf bank_mask:0xf bound_ctrl:1
	v_add_f32_dpp v52, v52, v52 quad_perm:[2,3,0,1] row_mask:0xf bank_mask:0xf bound_ctrl:1
	v_add_f32_dpp v53, v53, v53 quad_perm:[2,3,0,1] row_mask:0xf bank_mask:0xf bound_ctrl:1
	v_add_f32_dpp v54, v54, v54 quad_perm:[2,3,0,1] row_mask:0xf bank_mask:0xf bound_ctrl:1
	v_add_f32_dpp v55, v55, v55 quad_perm:[2,3,0,1] row_mask:0xf bank_mask:0xf bound_ctrl:1
	v_add_f32_dpp v48, v48, v48 row_half_mirror row_mask:0xf bank_mask:0xf bound_ctrl:1
; #define LAS __attribute__((address_space(3)))
; __device__ __forceinline__ float bf2f(bf16 v) { return __uint_as_float(((unsigned)v) << 16); }
; __device__ __forceinline__ unsigned f2bf(float f) { unsigned u = __float_as_uint(f); return (u + 0x7fffu + ((u >> 16) & 1u)) >> 16; }
; __device__ __forceinline__ float siluf_(float x) { return x / (1.0f + __expf(-x)); }
; __device__ __forceinline__ int wy_producer_task(const Ctx& c, int l, int tk, WyPre& P, unsigned* head) {
;     ...
; #pragma unroll
;     for (int j = 0; j < 3; ++j) { float xv[11];
; #pragma unroll
;         for (int r = 0; r < 11; ++r) xv[r] = bf2f((bf16)P.hx[j][r]);
; #pragma unroll
;         for (int r = 0; r < 8; ++r) { const int i = 8 * wid + r;
;             float y = siluf_(P.cw[j][0] * xv[r] + P.cw[j][1] * xv[r + 1] + P.cw[j][2] * xv[r + 2] + P.cw[j][3] * xv[r + 3]);
;             if (j < 2) y *= rsqrtf(wave_sum_fast(y * y) + RMS_EPS) * (j == 0 ? 0.125f : 1.0f);
;             if (j == 0) QF[i * 65 + lane] = y;
;             else if (j == 1) { KF[i * 65 + lane] = y; *(LAS bf16*)(KIMG + (lane >> 3) * 1024 + i * 16 + (lane & 7) * 2) = (bf16)f2bf(y); }
;             else VF[i * 65 + lane] = y; } }
	v_add_f32_dpp v49, v49, v49 row_half_mirror row_mask:0xf bank_mask:0xf bound_ctrl:1
	v_add_f32_dpp v50, v50, v50 row_half_mirror row_mask:0xf bank_mask:0xf bound_ctrl:1
	v_add_f32_dpp v51, v51, v51 row_half_mirror row_mask:0xf bank_mask:0xf bound_ctrl:1
	v_add_f32_dpp v52, v52, v52 row_half_mirror row_mask:0xf bank_mask:0xf bound_ctrl:1
	v_add_f32_dpp v53, v53, v53 row_half_mirror row_mask:0xf bank_mask:0xf bound_ctrl:1
	v_add_f32_dpp v54, v54, v54 row_half_mirror row_mask:0xf bank_mask:0xf bound_ctrl:1
	v_add_f32_dpp v55, v55, v55 row_half_mirror row_mask:0xf bank_mask:0xf bound_ctrl:1
	v_add_f32_dpp v48, v48, v48 row_mirror row_mask:0xf bank_mask:0xf bound_ctrl:1
	v_add_f32_dpp v49, v49, v49 row_mirror row_mask:0xf bank_mask:0xf bound_ctrl:1
	v_add_f32_dpp v50, v50, v50 row_mirror row_mask:0xf bank_mask:0xf bound_ctrl:1
	v_add_f32_dpp v51, v51, v51 row_mirror row_mask:0xf bank_mask:0xf bound_ctrl:1
	v_add_f32_dpp v52, v52, v52 row_mirror row_mask:0xf bank_mask:0xf bound_ctrl:1
	v_add_f32_dpp v53, v53, v53 row_mirror row_mask:0xf bank_mask:0xf bound_ctrl:1
	v_add_f32_dpp v54, v54, v54 row_mirror row_mask:0xf bank_mask:0xf bound_ctrl:1
	v_add_f32_dpp v55, v55, v55 row_mirror row_mask:0xf bank_mask:0xf bound_ctrl:1
	v_permlane16_swap_b32_e32 v48, v49
	v_permlane16_swap_b32_e32 v50, v51
	v_permlane16_swap_b32_e32 v52, v53
	v_permlane16_swap_b32_e32 v54, v55
	v_add_f32_e32 v48, v48, v49
	v_add_f32_e32 v50, v50, v51
	v_add_f32_e32 v52, v52, v53
	v_add_f32_e32 v54, v54, v55
	s_nop 1
	v_permlane32_swap_b32_e32 v48, v50
	v_permlane32_swap_b32_e32 v52, v54
	v_add_f32_e32 v48, v48, v50
	v_add_f32_e32 v52, v52, v54
	v_add_f32_e32 v48, 0x358637bd, v48
	v_add_f32_e32 v52, 0x358637bd, v52
	v_rsq_f32_e32 v48, v48
	v_rsq_f32_e32 v52, v52
	s_nop 0
	s_nop 1
	v_readlane_b32 s2, v48, 0
	v_readlane_b32 s3, v48, 16
	v_readlane_b32 s6, v48, 32
	v_readlane_b32 s7, v48, 48
	v_mul_f32_e32 v32, s2, v32
	v_mul_f32_e32 v33, s3, v33
	v_mul_f32_e32 v34, s6, v34
	v_mul_f32_e32 v35, s7, v35
	v_readlane_b32 s2, v52, 0
	v_readlane_b32 s3, v52, 16
	v_readlane_b32 s6, v52, 32
	v_readlane_b32 s7, v52, 48
	v_mul_f32_e32 v36, s2, v36
	v_mul_f32_e32 v37, s3, v37
	v_mul_f32_e32 v38, s6, v38
	v_mul_f32_e32 v39, s7, v39
	ds_write_b32 v2, v32 offset:0
	ds_write_b32 v2, v33 offset:260
	ds_write_b32 v2, v34 offset:520
	ds_write_b32 v2, v35 offset:780
	ds_write_b32 v2, v36 offset:1040
	ds_write_b32 v2, v37 offset:1300
	ds_write_b32 v2, v38 offset:1560
	ds_write_b32 v2, v39 offset:1820
	v_bfe_u32 v40, v32, 16, 1
	v_bfe_u32 v41, v33, 16, 1
	v_bfe_u32 v42, v34, 16, 1
	v_bfe_u32 v43, v35, 16, 1
	v_bfe_u32 v44, v36, 16, 1
	v_bfe_u32 v45, v37, 16, 1
	v_bfe_u32 v46, v38, 16, 1
	v_bfe_u32 v47, v39, 16, 1
	v_add3_u32 v40, v32, v40, s15
	v_add3_u32 v41, v33, v41, s15
	v_add3_u32 v42, v34, v42, s15
	v_add3_u32 v43, v35, v43, s15
	v_add3_u32 v44, v36, v44, s15
	v_add3_u32 v45, v37, v45, s15
	v_add3_u32 v46, v38, v46, s15
	v_add3_u32 v47, v39, v47, s15
	ds_write_b16_d16_hi v4, v40 offset:0
	ds_write_b16_d16_hi v4, v41 offset:16
	ds_write_b16_d16_hi v4, v42 offset:32
	ds_write_b16_d16_hi v4, v43 offset:48
	ds_write_b16_d16_hi v4, v44 offset:64
	ds_write_b16_d16_hi v4, v45 offset:80
	ds_write_b16_d16_hi v4, v46 offset:96
	ds_write_b16_d16_hi v4, v47 offset:112
	s_waitcnt vmcnt(0)
	v_lshlrev_b32_e32 v20, 16, v98
	v_lshlrev_b32_e32 v21, 16, v97
	v_lshlrev_b32_e32 v22, 16, v100
	v_lshlrev_b32_e32 v23, 16, v99
	v_lshlrev_b32_e32 v24, 16, v101
	v_lshlrev_b32_e32 v25, 16, v102
	v_lshlrev_b32_e32 v26, 16, v104
	v_lshlrev_b32_e32 v27, 16, v103
	v_lshlrev_b32_e32 v28, 16, v105
	v_lshlrev_b32_e32 v29, 16, v106
	v_lshlrev_b32_e32 v30, 16, v107
	v_mul_f32_e32 v32, v108, v20
	v_mul_f32_e32 v33, v108, v21
	v_mul_f32_e32 v34, v108, v22
	v_mul_f32_e32 v35, v108, v23
	v_mul_f32_e32 v36, v108, v24
	v_mul_f32_e32 v37, v108, v25
	v_mul_f32_e32 v38, v108, v26
	v_mul_f32_e32 v39, v108, v27
	v_fmac_f32_e32 v32, v110, v21
	v_fmac_f32_e32 v33, v110, v22
	v_fmac_f32_e32 v34, v110, v23
	v_fmac_f32_e32 v35, v110, v24
	v_fmac_f32_e32 v36, v110, v25
	v_fmac_f32_e32 v37, v110, v26
	v_fmac_f32_e32 v38, v110, v27
	v_fmac_f32_e32 v39, v110, v28
	v_fmac_f32_e32 v32, v112, v22
	v_fmac_f32_e32 v33, v112, v23
	v_fmac_f32_e32 v34, v112, v24
	v_fmac_f32_e32 v35, v112, v25
	v_fmac_f32_e32 v36, v112, v26
	v_fmac_f32_e32 v37, v112, v27
	v_fmac_f32_e32 v38, v112, v28
	v_fmac_f32_e32 v39, v112, v29
	v_fmac_f32_e32 v32, v113, v23
	v_fmac_f32_e32 v33, v113, v24
	v_fmac_f32_e32 v34, v113, v25
	v_fmac_f32_e32 v35, v113, v26
	v_fmac_f32_e32 v36, v113, v27
	v_fmac_f32_e32 v37, v113, v28
	v_fmac_f32_e32 v38, v113, v29
	v_fmac_f32_e32 v39, v113, v30
	v_pk_mul_f32 v[40:41], v[32:33], v[66:67] op_sel_hi:[1,0]
	v_pk_mul_f32 v[42:43], v[34:35], v[66:67] op_sel_hi:[1,0]
	v_pk_mul_f32 v[44:45], v[36:37], v[66:67] op_sel_hi:[1,0]
	v_pk_mul_f32 v[46:47], v[38:39], v[66:67] op_sel_hi:[1,0]
	v_exp_f32_e32 v40, v40
	v_exp_f32_e32 v41, v41
	v_exp_f32_e32 v42, v42
	v_exp_f32_e32 v43, v43
	v_exp_f32_e32 v44, v44
	v_exp_f32_e32 v45, v45
	v_exp_f32_e32 v46, v46
	v_exp_f32_e32 v47, v47
	v_pk_add_f32 v[40:41], v[40:41], v[66:67] op_sel:[0,1] op_sel_hi:[1,1]
	v_pk_add_f32 v[42:43], v[42:43], v[66:67] op_sel:[0,1] op_sel_hi:[1,1]
	v_pk_add_f32 v[44:45], v[44:45], v[66:67] op_sel:[0,1] op_sel_hi:[1,1]
	v_pk_add_f32 v[46:47], v[46:47], v[66:67] op_sel:[0,1] op_sel_hi:[1,1]
	v_rcp_f32_e32 v40, v40
	v_rcp_f32_e32 v41, v41
	v_rcp_f32_e32 v42, v42
	v_rcp_f32_e32 v43, v43
	v_rcp_f32_e32 v44, v44
	v_rcp_f32_e32 v45, v45
	v_rcp_f32_e32 v46, v46
	v_rcp_f32_e32 v47, v47
	v_pk_mul_f32 v[32:33], v[32:33], v[40:41]
	v_pk_mul_f32 v[34:35], v[34:35], v[42:43]
	v_pk_mul_f32 v[36:37], v[36:37], v[44:45]
	v_pk_mul_f32 v[38:39], v[38:39], v[46:47]
	ds_write_b32 v3, v32 offset:0
	ds_write_b32 v3, v33 offset:260
	ds_write_b32 v3, v34 offset:520
	ds_write_b32 v3, v35 offset:780
	ds_write_b32 v3, v36 offset:1040
	ds_write_b32 v3, v37 offset:1300
	ds_write_b32 v3, v38 offset:1560
	ds_write_b32 v3, v39 offset:1820
	s_and_b64 vcc, exec, s[38:39]
	s_cbranch_vccz .LBB0_1093
	s_and_saveexec_b64 s[2:3], s[4:5]
